# phase 4: GEMM tiles claimed dynamically per XCD group so the copier blocks take tiles once the copy queue is empty; phase-1 copiers stop at 761 tiles
# speedup vs baseline: 1.0406x; 1.0102x over previous
.Lcp1_entry:
	v_readfirstlane_b32 s0, v192
	v_lshlrev_b32_e32 v16, 4, v192
	s_add_u32 s4, s38, 0xc7b7100
	s_addc_u32 s5, s39, 0
	s_add_u32 s6, s38, 0xc7b7200
	s_addc_u32 s7, s39, 0
	s_lshr_b32 s0, s0, 6
	s_mov_b32 s1, 0
	s_mov_b32 s30, 2
	v_mov_b32_e32 v93, 0
	v_mov_b32_e32 v94, 1
	v_mov_b32_e32 v95, 16
	v_mov_b32_e32 v96, 20
	v_add_u32_e32 v17, 0x2000, v16
	v_add_u32_e32 v18, 0x4000, v16
	v_add_u32_e32 v19, 0x6000, v16
	v_add_u32_e32 v20, 0x8000, v16
	v_add_u32_e32 v21, 0xa000, v16
	v_add_u32_e32 v22, 0xc000, v16
	v_add_u32_e32 v23, 0xe000, v16
	v_add_u32_e32 v104, 0x10000, v16
	v_add_u32_e32 v105, 0x12000, v16
	v_add_u32_e32 v106, 0x14000, v16
	v_add_u32_e32 v107, 0x16000, v16
	v_add_u32_e32 v108, 0x18000, v16
	v_add_u32_e32 v109, 0x1a000, v16
	v_add_u32_e32 v110, 0x1c000, v16
	v_add_u32_e32 v111, 0x1e000, v16
	s_barrier
	s_cmp_lg_u32 s0, 0
	s_cbranch_scc1 .Lcp1_p0
	s_mov_b64 s[22:23], exec
	s_mov_b64 exec, 1
	global_load_dword v118, v93, s[6:7] sc1
	v_mov_b32_e32 v117, 0xa80
	s_waitcnt vmcnt(0)
	v_readfirstlane_b32 s25, v118
	s_cmpk_gt_u32 s25, 0x2f8
	s_cbranch_scc1 .Lcp1_pnone
	v_mov_b32_e32 v117, 2
	global_atomic_add v117, v93, v117, s[4:5] sc0
	s_waitcnt vmcnt(0)

.Lcp1_ac_A_j:
	s_lshl_b32 s18, s18, 17
	v_add_u32_e32 v92, s24, v16
	s_add_u32 s14, s36, s19
	s_addc_u32 s15, s37, 0
	s_add_u32 s14, s14, s18
	s_addc_u32 s15, s15, 0
	s_add_u32 s12, s12, s18
	s_addc_u32 s13, s13, 0
	s_add_u32 s12, s12, 0x2000
	s_addc_u32 s13, s13, 0
	global_load_dwordx4 v[180:183], v16, s[12:13] nt
	global_load_dwordx4 v[184:187], v17, s[12:13] nt
	global_load_dwordx4 v[188:191], v18, s[12:13] nt
	global_load_dwordx4 v[196:199], v19, s[12:13] nt
	global_load_dwordx4 v[200:203], v20, s[12:13] nt
	global_load_dwordx4 v[204:207], v21, s[12:13] nt
	global_load_dwordx4 v[208:211], v22, s[12:13] nt
	global_load_dwordx4 v[212:215], v23, s[12:13] nt
	global_load_dwordx4 v[216:219], v104, s[12:13] nt
	global_load_dwordx4 v[220:223], v105, s[12:13] nt
	global_load_dwordx4 v[224:227], v106, s[12:13] nt
	global_load_dwordx4 v[228:231], v107, s[12:13] nt
	global_load_dwordx4 v[244:247], v108, s[12:13] nt
	global_load_dwordx4 v[248:251], v109, s[12:13] nt
	global_load_dwordx4 v[4:7], v110, s[12:13] nt
	global_load_dwordx4 v[8:11], v92, s[12:13] nt
	s_waitcnt vmcnt(31)
	global_store_dwordx4 v16, v[30:33], s[10:11] nt
	s_waitcnt vmcnt(31)
	global_store_dwordx4 v17, v[34:37], s[10:11] nt
	s_waitcnt vmcnt(31)
	global_store_dwordx4 v18, v[38:41], s[10:11] nt
	s_waitcnt vmcnt(31)
	global_store_dwordx4 v19, v[42:45], s[10:11] nt
	s_waitcnt vmcnt(31)
	global_store_dwordx4 v20, v[46:49], s[10:11] nt
	s_waitcnt vmcnt(31)
	global_store_dwordx4 v21, v[50:53], s[10:11] nt
	s_waitcnt vmcnt(31)
	global_store_dwordx4 v22, v[54:57], s[10:11] nt
	s_waitcnt vmcnt(31)
	global_store_dwordx4 v23, v[58:61], s[10:11] nt
	s_waitcnt vmcnt(31)
	global_store_dwordx4 v104, v[62:65], s[10:11] nt
	s_waitcnt vmcnt(31)
	global_store_dwordx4 v105, v[66:69], s[10:11] nt
	s_waitcnt vmcnt(31)
	global_store_dwordx4 v106, v[70:73], s[10:11] nt
	s_waitcnt vmcnt(31)
	global_store_dwordx4 v107, v[74:77], s[10:11] nt
	s_waitcnt vmcnt(31)
	global_store_dwordx4 v108, v[164:167], s[10:11] nt
	s_waitcnt vmcnt(31)
	global_store_dwordx4 v109, v[168:171], s[10:11] nt
	s_waitcnt vmcnt(31)
	global_store_dwordx4 v110, v[172:175], s[10:11] nt
	s_waitcnt vmcnt(31)
	global_store_dwordx4 v91, v[176:179], s[10:11] nt
	s_cmp_lg_u32 s0, 0
	s_cbranch_scc1 .Lcp1_A_s4
	s_mov_b64 s[22:23], exec
	s_mov_b64 exec, 1
	s_cmp_lg_u32 s1, 0
	s_cbranch_scc1 .Lcp1_A_s4stop
	s_waitcnt vmcnt(32)
	v_readfirstlane_b32 s25, v118
	s_cmpk_gt_u32 s25, 0x2f8
	s_cselect_b32 s1, 1, 0
	v_readfirstlane_b32 s26, v117
	s_cmpk_ge_u32 s26, 0xa80
	s_cselect_b32 s27, 1, 0
	s_or_b32 s1, s1, s27
	s_branch .Lcp1_A_s4pub

.Lcp1_ac_B_j:
	s_lshl_b32 s18, s18, 17
	v_add_u32_e32 v91, s24, v16
	s_add_u32 s10, s36, s19
	s_addc_u32 s11, s37, 0
	s_add_u32 s10, s10, s18
	s_addc_u32 s11, s11, 0
	s_add_u32 s8, s8, s18
	s_addc_u32 s9, s9, 0
	s_add_u32 s8, s8, 0x2000
	s_addc_u32 s9, s9, 0
	global_load_dwordx4 v[30:33], v16, s[8:9] nt
	global_load_dwordx4 v[34:37], v17, s[8:9] nt
	global_load_dwordx4 v[38:41], v18, s[8:9] nt
	global_load_dwordx4 v[42:45], v19, s[8:9] nt
	global_load_dwordx4 v[46:49], v20, s[8:9] nt
	global_load_dwordx4 v[50:53], v21, s[8:9] nt
	global_load_dwordx4 v[54:57], v22, s[8:9] nt
	global_load_dwordx4 v[58:61], v23, s[8:9] nt
	global_load_dwordx4 v[62:65], v104, s[8:9] nt
	global_load_dwordx4 v[66:69], v105, s[8:9] nt
	global_load_dwordx4 v[70:73], v106, s[8:9] nt
	global_load_dwordx4 v[74:77], v107, s[8:9] nt
	global_load_dwordx4 v[164:167], v108, s[8:9] nt
	global_load_dwordx4 v[168:171], v109, s[8:9] nt
	global_load_dwordx4 v[172:175], v110, s[8:9] nt
	global_load_dwordx4 v[176:179], v91, s[8:9] nt
	s_waitcnt vmcnt(31)
	global_store_dwordx4 v16, v[180:183], s[14:15] nt
	s_waitcnt vmcnt(31)
	global_store_dwordx4 v17, v[184:187], s[14:15] nt
	s_waitcnt vmcnt(31)
	global_store_dwordx4 v18, v[188:191], s[14:15] nt
	s_waitcnt vmcnt(31)
	global_store_dwordx4 v19, v[196:199], s[14:15] nt
	s_waitcnt vmcnt(31)
	global_store_dwordx4 v20, v[200:203], s[14:15] nt
	s_waitcnt vmcnt(31)
	global_store_dwordx4 v21, v[204:207], s[14:15] nt
	s_waitcnt vmcnt(31)
	global_store_dwordx4 v22, v[208:211], s[14:15] nt
	s_waitcnt vmcnt(31)
	global_store_dwordx4 v23, v[212:215], s[14:15] nt
	s_waitcnt vmcnt(31)
	global_store_dwordx4 v104, v[216:219], s[14:15] nt
	s_waitcnt vmcnt(31)
	global_store_dwordx4 v105, v[220:223], s[14:15] nt
	s_waitcnt vmcnt(31)
	global_store_dwordx4 v106, v[224:227], s[14:15] nt
	s_waitcnt vmcnt(31)
	global_store_dwordx4 v107, v[228:231], s[14:15] nt
	s_waitcnt vmcnt(31)
	global_store_dwordx4 v108, v[244:247], s[14:15] nt
	s_waitcnt vmcnt(31)
	global_store_dwordx4 v109, v[248:251], s[14:15] nt
	s_waitcnt vmcnt(31)
	global_store_dwordx4 v110, v[4:7], s[14:15] nt
	s_waitcnt vmcnt(31)
	global_store_dwordx4 v92, v[8:11], s[14:15] nt
	s_cmp_lg_u32 s0, 0
	s_cbranch_scc1 .Lcp1_B_s4
	s_mov_b64 s[22:23], exec
	s_mov_b64 exec, 1
	s_cmp_lg_u32 s1, 0
	s_cbranch_scc1 .Lcp1_B_s4stop
	s_waitcnt vmcnt(32)
	v_readfirstlane_b32 s25, v118
	s_cmpk_gt_u32 s25, 0x2f8
	s_cselect_b32 s1, 1, 0
	v_readfirstlane_b32 s26, v117
	s_cmpk_ge_u32 s26, 0xa80
	s_cselect_b32 s27, 1, 0
	s_or_b32 s1, s1, s27
	s_branch .Lcp1_B_s4pub

.LBB0_1154:
	s_or_b64 exec, exec, s[0:1]
	s_min_i32 s3, s3, 0x88
	s_cmp_ge_i32 s2, s3
	s_mov_b64 s[0:1], -1
	s_waitcnt lgkmcnt(0)
	s_barrier
	s_barrier
	s_cmp_lg_u32 s34, 0x20000
	s_cbranch_scc1 .Lp4_orig
	s_and_b32 s57, s2, 7
	s_mul_i32 s58, s57, 34
	s_lshl_b32 s60, s57, 6
	s_add_u32 s60, s60, 0xc7b7500
	s_add_u32 s60, s38, s60
	s_addc_u32 s61, s39, 0
	s_cmpk_ge_u32 s2, 0x88
	s_cselect_b32 s59, 1, 0
	s_cbranch_scc1 .Lcpd_entry
	v_readlane_b32 s2, v255, 0
	s_add_u32 s2, s58, s2
	s_branch .LBB0_1182
.Lp4_orig:
	s_mov_b32 s59, 2
	s_cmp_ge_i32 s2, s3
	s_cbranch_scc0 .LBB0_1178
	s_branch .Lcpd_entry

.LBB0_1183:
	s_or_b64 exec, exec, s[26:27]
	s_cmp_eq_u32 s59, 2
	s_cbranch_scc1 .Lp4_static
.Lp4c_b:
	s_barrier
	v_readfirstlane_b32 s62, v192
	v_mov_b32_e32 v238, 8
	s_cmp_lt_u32 s62, 64
	s_cbranch_scc0 .Lp4c_b_w
	s_mov_b64 s[64:65], exec
	s_mov_b64 exec, 1
	v_mov_b32_e32 v236, 0
	v_mov_b32_e32 v237, 1
	global_atomic_add v237, v236, v237, s[60:61] sc0
	s_waitcnt vmcnt(0)
	ds_write_b32 v238, v237
	s_waitcnt lgkmcnt(0)
	s_mov_b64 exec, s[64:65]
.Lp4c_b_w:
	s_barrier
	ds_read_b32 v239, v238
	s_waitcnt lgkmcnt(0)
	v_readfirstlane_b32 s62, v239
	s_cmp_ge_u32 s62, 17
	s_cbranch_scc1 .Lp4_tdone
	s_add_u32 s2, s58, s62
	s_add_u32 s2, s2, 17
	s_mov_b32 s54, s2
	s_branch .LBB0_1184
.Lp4_tdone:
	s_cmp_eq_u32 s59, 0
	s_cbranch_scc0 .LBB0_1213
	s_mov_b32 s59, 2
	s_branch .Lcpd_entry
.Lp4_static:
	s_add_i32 s2, s2, s3
	s_add_i32 s54, s54, s3
	s_cmp_ge_i32 s2, s33
	s_cbranch_scc1 .LBB0_1193

.Lcpd_exit:
	s_cmp_eq_u32 s59, 1
	s_cbranch_scc0 .LBB0_1213
	s_mov_b32 s59, 3

.Lp4c_x_w:
	s_barrier
	ds_read_b32 v239, v238
	s_waitcnt lgkmcnt(0)
	v_readfirstlane_b32 s62, v239
	s_cmp_ge_u32 s62, 17
	s_cbranch_scc1 .LBB0_1213
	s_add_u32 s2, s58, s62
	s_add_u32 s2, s2, 17
	s_branch .LBB0_1182
